# v143 + P4 epilogue residual-x loads software-pipelined one token round ahead (scripts/p4_epi_pipe.py)
# speedup vs baseline: 1.0014x; 1.0014x over previous
.LBB0_318:
	s_or_b64 exec, exec, s[46:47]
	v_and_b32_e32 v131, 64, v164
	v_xor_b32_e32 v130, 16, v164
	v_add_u32_e32 v131, 64, v131
	v_cmp_lt_i32_e32 vcc, v130, v131
	v_lshl_or_b32 v150, s16, 8, v1
	v_lshl_or_b32 v152, s38, 8, v147
	v_cndmask_b32_e32 v130, v164, v130, vcc
	v_lshlrev_b32_e32 v167, 2, v130
	v_xor_b32_e32 v130, 32, v164
	v_cmp_lt_i32_e32 vcc, v130, v131
	s_waitcnt vmcnt(0)
	s_barrier
	v_mbcnt_lo_u32_b32 v204, -1, 0
	v_mbcnt_hi_u32_b32 v204, -1, v204
	v_bfe_u32 v204, v204, 4, 1
	v_mul_u32_u24_e32 v204, 24, v204
	v_mov_b32_e32 v205, 0
	v_cndmask_b32_e32 v130, v164, v130, vcc
	v_lshlrev_b32_e32 v166, 2, v130
	v_ashrrev_i32_e32 v151, 31, v150
	s_lshl_b32 s46, s16, 2
	v_ashrrev_i32_e32 v153, 31, v152
	v_readlane_b32 s60, v249, 38
	v_lshlrev_b64 v[130:131], 12, v[152:153]
	v_readlane_b32 s61, v249, 39
	v_lshlrev_b64 v[154:155], 11, v[152:153]
	v_lshl_add_u64 v[154:155], s[12:13], 0, v[154:155]
	v_lshl_add_u64 v[130:131], s[60:61], 0, v[130:131]
	v_lshl_add_u64 v[130:131], v[150:151], 2, v[130:131]
	s_mov_b64 s[100:101], 0x10000
	v_lshl_add_u64 v[242:243], s[100:101], 0, v[130:131]
	global_load_dwordx4 v[168:171], v[130:131], off
	global_load_dwordx4 v[172:175], v[130:131], off offset:64
	global_load_dwordx4 v[176:179], v[130:131], off offset:128
	global_load_dwordx4 v[180:183], v[130:131], off offset:192
	global_load_dwordx4 v[142:145], v[130:131], off offset:512
	global_load_dwordx4 v[138:141], v[130:131], off offset:576
	global_load_dwordx4 v[134:137], v[130:131], off offset:640
	s_nop 0
	global_load_dwordx4 v[130:133], v[130:131], off offset:704
	global_load_dwordx4 v[206:209], v[242:243], off
	global_load_dwordx4 v[210:213], v[242:243], off offset:64
	global_load_dwordx4 v[214:217], v[242:243], off offset:128
	global_load_dwordx4 v[218:221], v[242:243], off offset:192
	global_load_dwordx4 v[222:225], v[242:243], off offset:512
	global_load_dwordx4 v[226:229], v[242:243], off offset:576
	global_load_dwordx4 v[230:233], v[242:243], off offset:640
	global_load_dwordx4 v[234:237], v[242:243], off offset:704
	v_lshlrev_b64 v[184:185], 6, v[152:153]
	v_lshl_add_u64 v[154:155], v[150:151], 1, v[154:155]
	v_lshlrev_b32_e32 v148, 2, v146
	v_readlane_b32 s62, v249, 40
	v_readlane_b32 s63, v249, 41
	v_readlane_b32 s64, v249, 42
	v_readlane_b32 s65, v249, 43
	v_readlane_b32 s66, v249, 44
	v_readlane_b32 s67, v249, 45
	v_readlane_b32 s68, v249, 46
	v_readlane_b32 s69, v249, 47
	v_readlane_b32 s70, v249, 48
	v_readlane_b32 s71, v249, 49
	v_readlane_b32 s72, v249, 50
	v_readlane_b32 s73, v249, 51
	v_readlane_b32 s74, v249, 52
	v_readlane_b32 s75, v249, 53
	s_waitcnt vmcnt(15)
	v_pk_add_f32 v[118:119], v[118:119], v[168:169]
	v_pk_add_f32 v[120:121], v[120:121], v[170:171]
	s_waitcnt vmcnt(14)
	v_pk_add_f32 v[122:123], v[122:123], v[172:173]
	v_pk_add_f32 v[124:125], v[124:125], v[174:175]
	s_waitcnt vmcnt(13)
	v_pk_add_f32 v[126:127], v[126:127], v[176:177]
	s_waitcnt vmcnt(12)
	v_pk_add_f32 v[168:169], v[116:117], v[182:183]
	v_pk_mul_f32 v[116:117], v[118:119], v[118:119]
	v_pk_mul_f32 v[170:171], v[120:121], v[120:121]
	v_cvt_pk_bf16_f32 v186, v118, v119
	v_cvt_pk_bf16_f32 v187, v120, v121
	v_pk_mul_f32 v[120:121], v[122:123], v[122:123]
	v_pk_add_f32 v[128:129], v[128:129], v[178:179]
	v_pk_add_f32 v[114:115], v[114:115], v[180:181]
	v_pk_mul_f32 v[172:173], v[124:125], v[124:125]
	v_cvt_pk_bf16_f32 v188, v122, v123
	v_cvt_pk_bf16_f32 v189, v124, v125
	v_pk_mul_f32 v[124:125], v[126:127], v[126:127]
	v_add_f32_e32 v120, v120, v121
	v_add_f32_e32 v116, v116, v117
	v_pk_mul_f32 v[174:175], v[128:129], v[128:129]
	v_cvt_pk_bf16_f32 v190, v126, v127
	v_cvt_pk_bf16_f32 v191, v128, v129
	v_pk_mul_f32 v[128:129], v[114:115], v[114:115]
	v_add_f32_e32 v117, v124, v125
	v_add_f32_e32 v120, v120, v172
	v_add_f32_e32 v116, v116, v170
	v_pk_mul_f32 v[176:177], v[168:169], v[168:169]
	v_add_f32_e32 v121, v128, v129
	v_add_f32_e32 v117, v117, v174
	v_add_f32_e32 v120, v120, v173
	v_add_f32_e32 v116, v116, v171
	v_add_f32_e32 v121, v121, v176
	v_add_f32_e32 v117, v117, v175
	v_add_f32_e32 v116, v116, v120
	v_add_f32_e32 v116, v116, v117
	v_add_f32_e32 v117, v121, v177
	v_add_f32_e32 v116, v116, v117
	ds_bpermute_b32 v117, v167, v116
	v_cvt_pk_bf16_f32 v192, v114, v115
	v_cvt_pk_bf16_f32 v193, v168, v169
	s_nop 1
	v_permlane16_swap_b32_e32 v186, v188
	v_permlane16_swap_b32_e32 v187, v189
	v_permlane16_swap_b32_e32 v190, v192
	v_permlane16_swap_b32_e32 v191, v193
	v_lshl_add_u64 v[202:203], v[154:155], 0, v[204:205]
	global_store_dwordx4 v[202:203], v[186:189], off sc1
	global_store_dwordx4 v[202:203], v[190:193], off offset:64 sc1
	s_waitcnt lgkmcnt(0)
	v_add_f32_e32 v116, v116, v117
	ds_bpermute_b32 v117, v166, v116
	v_lshl_add_u64 v[114:115], s[90:91], 0, v[184:185]
	s_and_saveexec_b64 s[38:39], s[8:9]
	s_cbranch_execz .LBB0_320
	s_lshl_b32 s16, s46, 2
	s_waitcnt lgkmcnt(0)
	v_add_f32_e32 v118, v116, v117
	v_lshl_add_u64 v[116:117], v[114:115], 0, s[16:17]
	v_lshl_add_u64 v[116:117], v[116:117], 0, v[148:149]
	global_store_dword v[116:117], v118, off sc1
.LBB0_320:
	s_or_b64 exec, exec, s[38:39]
	s_waitcnt vmcnt(13)
	v_pk_add_f32 v[110:111], v[110:111], v[142:143]
	v_pk_add_f32 v[112:113], v[112:113], v[144:145]
	s_waitcnt lgkmcnt(0)
	v_pk_mul_f32 v[116:117], v[110:111], v[110:111]
	v_cvt_pk_bf16_f32 v194, v110, v111
	v_cvt_pk_bf16_f32 v195, v112, v113
	s_waitcnt vmcnt(12)
	v_pk_add_f32 v[106:107], v[106:107], v[138:139]
	v_pk_add_f32 v[108:109], v[108:109], v[140:141]
	v_pk_mul_f32 v[110:111], v[106:107], v[106:107]
	v_pk_mul_f32 v[118:119], v[112:113], v[112:113]
	v_pk_mul_f32 v[112:113], v[108:109], v[108:109]
	v_cvt_pk_bf16_f32 v196, v106, v107
	v_add_f32_e32 v107, v110, v111
	v_add_f32_e32 v110, v116, v117
	s_waitcnt vmcnt(11)
	v_pk_add_f32 v[102:103], v[102:103], v[134:135]
	v_add_f32_e32 v107, v107, v112
	v_add_f32_e32 v110, v110, v118
	v_pk_add_f32 v[104:105], v[104:105], v[136:137]
	v_pk_mul_f32 v[120:121], v[102:103], v[102:103]
	s_waitcnt vmcnt(10)
	v_pk_add_f32 v[124:125], v[98:99], v[130:131]
	v_add_f32_e32 v107, v107, v113
	v_add_f32_e32 v110, v110, v119
	v_pk_mul_f32 v[122:123], v[104:105], v[104:105]
	v_pk_add_f32 v[100:101], v[100:101], v[132:133]
	v_pk_mul_f32 v[98:99], v[124:125], v[124:125]
	v_add_f32_e32 v107, v110, v107
	v_add_f32_e32 v110, v120, v121
	v_pk_mul_f32 v[126:127], v[100:101], v[100:101]
	v_add_f32_e32 v110, v110, v122
	v_add_f32_e32 v98, v98, v99
	v_add_f32_e32 v110, v110, v123
	v_add_f32_e32 v98, v98, v126
	v_add_f32_e32 v107, v107, v110
	v_add_f32_e32 v98, v98, v127
	v_add_f32_e32 v98, v107, v98
	ds_bpermute_b32 v99, v167, v98
	v_cvt_pk_bf16_f32 v197, v108, v109
	v_cvt_pk_bf16_f32 v198, v102, v103
	v_cvt_pk_bf16_f32 v199, v104, v105
	s_waitcnt lgkmcnt(0)
	v_add_f32_e32 v98, v98, v99
	ds_bpermute_b32 v99, v166, v98
	v_cvt_pk_bf16_f32 v200, v124, v125
	v_cvt_pk_bf16_f32 v201, v100, v101
	s_nop 1
	v_permlane16_swap_b32_e32 v194, v196
	v_permlane16_swap_b32_e32 v195, v197
	v_permlane16_swap_b32_e32 v198, v200
	v_permlane16_swap_b32_e32 v199, v201
	v_lshl_add_u64 v[202:203], v[154:155], 0, v[204:205]
	global_store_dwordx4 v[202:203], v[194:197], off offset:256 sc1
	global_store_dwordx4 v[202:203], v[198:201], off offset:320 sc1
	s_and_saveexec_b64 s[38:39], s[8:9]
	s_cbranch_execz .LBB0_322
	s_lshl_b32 s16, s46, 2
	s_waitcnt lgkmcnt(0)
	v_add_f32_e32 v100, v98, v99
	v_lshl_add_u64 v[98:99], v[114:115], 0, s[16:17]
	v_lshl_add_u64 v[98:99], v[98:99], 0, v[148:149]
	global_store_dword v[98:99], v100, off offset:8 sc1
.LBB0_322:
	s_or_b64 exec, exec, s[38:39]
	s_mov_b64 s[100:101], 0x70000
	v_lshl_add_u64 v[242:243], s[100:101], 0, v[242:243]
	global_load_dwordx4 v[168:171], v[242:243], off
	global_load_dwordx4 v[172:175], v[242:243], off offset:64
	global_load_dwordx4 v[176:179], v[242:243], off offset:128
	global_load_dwordx4 v[180:183], v[242:243], off offset:192
	global_load_dwordx4 v[142:145], v[242:243], off offset:512
	global_load_dwordx4 v[138:141], v[242:243], off offset:576
	global_load_dwordx4 v[134:137], v[242:243], off offset:640
	global_load_dwordx4 v[130:133], v[242:243], off offset:704
	v_add_u32_e32 v114, 16, v152
	v_ashrrev_i32_e32 v115, 31, v114
	v_readlane_b32 s60, v249, 38
	s_waitcnt lgkmcnt(0)
	v_readlane_b32 s61, v249, 39
	v_lshlrev_b64 v[244:245], 11, v[114:115]
	v_lshlrev_b64 v[246:247], 6, v[114:115]
	v_lshl_add_u64 v[114:115], s[12:13], 0, v[244:245]
	v_lshl_add_u64 v[114:115], v[150:151], 1, v[114:115]
	v_readlane_b32 s62, v249, 40
	v_readlane_b32 s63, v249, 41
	v_readlane_b32 s64, v249, 42
	v_readlane_b32 s65, v249, 43
	v_readlane_b32 s66, v249, 44
	v_readlane_b32 s67, v249, 45
	v_readlane_b32 s68, v249, 46
	v_readlane_b32 s69, v249, 47
	v_readlane_b32 s70, v249, 48
	v_readlane_b32 s71, v249, 49
	v_readlane_b32 s72, v249, 50
	v_readlane_b32 s73, v249, 51
	v_readlane_b32 s74, v249, 52
	v_readlane_b32 s75, v249, 53
	s_waitcnt vmcnt(19)
	v_pk_add_f32 v[86:87], v[86:87], v[206:207]
	v_pk_add_f32 v[88:89], v[88:89], v[208:209]
	s_waitcnt vmcnt(18)
	v_pk_add_f32 v[90:91], v[90:91], v[210:211]
	v_pk_add_f32 v[92:93], v[92:93], v[212:213]
	s_waitcnt vmcnt(17)
	v_pk_add_f32 v[94:95], v[94:95], v[214:215]
	s_waitcnt vmcnt(16)
	v_pk_add_f32 v[206:207], v[84:85], v[220:221]
	v_pk_mul_f32 v[84:85], v[86:87], v[86:87]
	v_pk_mul_f32 v[208:209], v[88:89], v[88:89]
	v_cvt_pk_bf16_f32 v186, v86, v87
	v_cvt_pk_bf16_f32 v187, v88, v89
	v_pk_mul_f32 v[88:89], v[90:91], v[90:91]
	v_pk_add_f32 v[96:97], v[96:97], v[216:217]
	v_pk_add_f32 v[82:83], v[82:83], v[218:219]
	v_pk_mul_f32 v[210:211], v[92:93], v[92:93]
	v_cvt_pk_bf16_f32 v188, v90, v91
	v_cvt_pk_bf16_f32 v189, v92, v93
	v_pk_mul_f32 v[92:93], v[94:95], v[94:95]
	v_add_f32_e32 v88, v88, v89
	v_add_f32_e32 v84, v84, v85
	v_pk_mul_f32 v[212:213], v[96:97], v[96:97]
	v_pk_mul_f32 v[214:215], v[82:83], v[82:83]
	v_add_f32_e32 v85, v92, v93
	v_add_f32_e32 v88, v88, v210
	v_add_f32_e32 v84, v84, v208
	v_pk_mul_f32 v[216:217], v[206:207], v[206:207]
	v_add_f32_e32 v89, v214, v215
	v_add_f32_e32 v85, v85, v212
	v_add_f32_e32 v88, v88, v211
	v_add_f32_e32 v84, v84, v209
	v_add_f32_e32 v89, v89, v216
	v_add_f32_e32 v85, v85, v213
	v_add_f32_e32 v84, v84, v88
	v_add_f32_e32 v84, v84, v85
	v_add_f32_e32 v85, v89, v217
	v_add_f32_e32 v84, v84, v85
	ds_bpermute_b32 v85, v167, v84
	v_cvt_pk_bf16_f32 v192, v82, v83
	v_cvt_pk_bf16_f32 v193, v206, v207
	v_cvt_pk_bf16_f32 v190, v94, v95
	v_cvt_pk_bf16_f32 v191, v96, v97
	s_waitcnt lgkmcnt(0)
	v_add_f32_e32 v84, v84, v85
	ds_bpermute_b32 v85, v166, v84
	s_nop 1
	v_permlane16_swap_b32_e32 v186, v188
	v_permlane16_swap_b32_e32 v187, v189
	v_permlane16_swap_b32_e32 v190, v192
	v_permlane16_swap_b32_e32 v191, v193
	v_lshl_add_u64 v[202:203], v[114:115], 0, v[204:205]
	global_store_dwordx4 v[202:203], v[186:189], off sc1
	global_store_dwordx4 v[202:203], v[190:193], off offset:64 sc1
	v_lshl_add_u64 v[82:83], s[90:91], 0, v[246:247]
	s_and_saveexec_b64 s[38:39], s[8:9]
	s_cbranch_execz .LBB0_324
	s_lshl_b32 s16, s46, 2
	s_waitcnt lgkmcnt(0)
	v_add_f32_e32 v86, v84, v85
	v_lshl_add_u64 v[84:85], v[82:83], 0, s[16:17]
	v_lshl_add_u64 v[84:85], v[84:85], 0, v[148:149]
	global_store_dword v[84:85], v86, off sc1
.LBB0_324:
	s_or_b64 exec, exec, s[38:39]
	s_waitcnt vmcnt(17)
	v_pk_add_f32 v[78:79], v[78:79], v[222:223]
	v_pk_add_f32 v[80:81], v[80:81], v[224:225]
	s_waitcnt lgkmcnt(0)
	v_pk_mul_f32 v[84:85], v[78:79], v[78:79]
	v_cvt_pk_bf16_f32 v194, v78, v79
	v_cvt_pk_bf16_f32 v195, v80, v81
	s_waitcnt vmcnt(16)
	v_pk_add_f32 v[74:75], v[74:75], v[226:227]
	v_pk_add_f32 v[76:77], v[76:77], v[228:229]
	v_pk_mul_f32 v[78:79], v[74:75], v[74:75]
	v_pk_mul_f32 v[86:87], v[80:81], v[80:81]
	v_pk_mul_f32 v[80:81], v[76:77], v[76:77]
	v_cvt_pk_bf16_f32 v196, v74, v75
	v_add_f32_e32 v75, v78, v79
	v_add_f32_e32 v78, v84, v85
	s_waitcnt vmcnt(15)
	v_pk_add_f32 v[70:71], v[70:71], v[230:231]
	v_add_f32_e32 v75, v75, v80
	v_add_f32_e32 v78, v78, v86
	v_pk_add_f32 v[72:73], v[72:73], v[232:233]
	v_pk_mul_f32 v[88:89], v[70:71], v[70:71]
	s_waitcnt vmcnt(14)
	v_pk_add_f32 v[92:93], v[66:67], v[234:235]
	v_add_f32_e32 v75, v75, v81
	v_add_f32_e32 v78, v78, v87
	v_pk_mul_f32 v[90:91], v[72:73], v[72:73]
	v_pk_add_f32 v[68:69], v[68:69], v[236:237]
	v_pk_mul_f32 v[66:67], v[92:93], v[92:93]
	v_add_f32_e32 v75, v78, v75
	v_add_f32_e32 v78, v88, v89
	v_pk_mul_f32 v[94:95], v[68:69], v[68:69]
	v_add_f32_e32 v78, v78, v90
	v_add_f32_e32 v66, v66, v67
	v_add_f32_e32 v78, v78, v91
	v_add_f32_e32 v66, v66, v94
	v_add_f32_e32 v75, v75, v78
	v_add_f32_e32 v66, v66, v95
	v_add_f32_e32 v66, v75, v66
	ds_bpermute_b32 v67, v167, v66
	v_cvt_pk_bf16_f32 v197, v76, v77
	v_cvt_pk_bf16_f32 v198, v70, v71
	v_cvt_pk_bf16_f32 v199, v72, v73
	s_waitcnt lgkmcnt(0)
	v_add_f32_e32 v66, v66, v67
	ds_bpermute_b32 v67, v166, v66
	v_cvt_pk_bf16_f32 v200, v92, v93
	v_cvt_pk_bf16_f32 v201, v68, v69
	s_nop 1
	v_permlane16_swap_b32_e32 v194, v196
	v_permlane16_swap_b32_e32 v195, v197
	v_permlane16_swap_b32_e32 v198, v200
	v_permlane16_swap_b32_e32 v199, v201
	v_lshl_add_u64 v[202:203], v[114:115], 0, v[204:205]
	global_store_dwordx4 v[202:203], v[194:197], off offset:256 sc1
	global_store_dwordx4 v[202:203], v[198:201], off offset:320 sc1
	s_and_saveexec_b64 s[38:39], s[8:9]
	s_cbranch_execz .LBB0_326
	s_lshl_b32 s16, s46, 2
	s_waitcnt lgkmcnt(0)
	v_add_f32_e32 v68, v66, v67
	v_lshl_add_u64 v[66:67], v[82:83], 0, s[16:17]
	v_lshl_add_u64 v[66:67], v[66:67], 0, v[148:149]
	global_store_dword v[66:67], v68, off offset:8 sc1
.LBB0_326:
	s_or_b64 exec, exec, s[38:39]
	s_mov_b64 s[100:101], 0x10000
	v_lshl_add_u64 v[242:243], s[100:101], 0, v[242:243]
	global_load_dwordx4 v[206:209], v[242:243], off
	global_load_dwordx4 v[210:213], v[242:243], off offset:64
	global_load_dwordx4 v[214:217], v[242:243], off offset:128
	global_load_dwordx4 v[218:221], v[242:243], off offset:192
	global_load_dwordx4 v[222:225], v[242:243], off offset:512
	global_load_dwordx4 v[226:229], v[242:243], off offset:576
	global_load_dwordx4 v[230:233], v[242:243], off offset:640
	global_load_dwordx4 v[234:237], v[242:243], off offset:704
	v_add_u32_e32 v82, 0x80, v152
	v_ashrrev_i32_e32 v83, 31, v82
	v_readlane_b32 s60, v249, 38
	s_waitcnt lgkmcnt(0)
	v_readlane_b32 s61, v249, 39
	v_lshlrev_b64 v[100:101], 11, v[82:83]
	v_lshlrev_b64 v[102:103], 6, v[82:83]
	v_lshl_add_u64 v[82:83], s[12:13], 0, v[100:101]
	v_lshl_add_u64 v[82:83], v[150:151], 1, v[82:83]
	v_readlane_b32 s62, v249, 40
	v_readlane_b32 s63, v249, 41
	v_readlane_b32 s64, v249, 42
	v_readlane_b32 s65, v249, 43
	v_readlane_b32 s66, v249, 44
	v_readlane_b32 s67, v249, 45
	v_readlane_b32 s68, v249, 46
	v_readlane_b32 s69, v249, 47
	v_readlane_b32 s70, v249, 48
	v_readlane_b32 s71, v249, 49
	v_readlane_b32 s72, v249, 50
	v_readlane_b32 s73, v249, 51
	v_readlane_b32 s74, v249, 52
	v_readlane_b32 s75, v249, 53
	s_waitcnt vmcnt(19)
	v_pk_add_f32 v[54:55], v[54:55], v[168:169]
	v_pk_add_f32 v[56:57], v[56:57], v[170:171]
	s_waitcnt vmcnt(18)
	v_pk_add_f32 v[58:59], v[58:59], v[172:173]
	v_pk_add_f32 v[60:61], v[60:61], v[174:175]
	s_waitcnt vmcnt(17)
	v_pk_add_f32 v[62:63], v[62:63], v[176:177]
	s_waitcnt vmcnt(16)
	v_pk_add_f32 v[168:169], v[52:53], v[182:183]
	v_pk_mul_f32 v[52:53], v[54:55], v[54:55]
	v_pk_mul_f32 v[170:171], v[56:57], v[56:57]
	v_cvt_pk_bf16_f32 v186, v54, v55
	v_cvt_pk_bf16_f32 v187, v56, v57
	v_pk_mul_f32 v[56:57], v[58:59], v[58:59]
	v_pk_add_f32 v[64:65], v[64:65], v[178:179]
	v_pk_add_f32 v[50:51], v[50:51], v[180:181]
	v_pk_mul_f32 v[172:173], v[60:61], v[60:61]
	v_cvt_pk_bf16_f32 v188, v58, v59
	v_cvt_pk_bf16_f32 v189, v60, v61
	v_pk_mul_f32 v[60:61], v[62:63], v[62:63]
	v_add_f32_e32 v56, v56, v57
	v_add_f32_e32 v52, v52, v53
	v_pk_mul_f32 v[174:175], v[64:65], v[64:65]
	v_pk_mul_f32 v[176:177], v[50:51], v[50:51]
	v_add_f32_e32 v53, v60, v61
	v_add_f32_e32 v56, v56, v172
	v_add_f32_e32 v52, v52, v170
	v_pk_mul_f32 v[178:179], v[168:169], v[168:169]
	v_add_f32_e32 v57, v176, v177
	v_add_f32_e32 v53, v53, v174
	v_add_f32_e32 v56, v56, v173
	v_add_f32_e32 v52, v52, v171
	v_add_f32_e32 v57, v57, v178
	v_add_f32_e32 v53, v53, v175
	v_add_f32_e32 v52, v52, v56
	v_add_f32_e32 v52, v52, v53
	v_add_f32_e32 v53, v57, v179
	v_add_f32_e32 v52, v52, v53
	ds_bpermute_b32 v53, v167, v52
	v_cvt_pk_bf16_f32 v192, v50, v51
	v_cvt_pk_bf16_f32 v193, v168, v169
	v_cvt_pk_bf16_f32 v190, v62, v63
	v_cvt_pk_bf16_f32 v191, v64, v65
	s_waitcnt lgkmcnt(0)
	v_add_f32_e32 v52, v52, v53
	ds_bpermute_b32 v53, v166, v52
	s_nop 1
	v_permlane16_swap_b32_e32 v186, v188
	v_permlane16_swap_b32_e32 v187, v189
	v_permlane16_swap_b32_e32 v190, v192
	v_permlane16_swap_b32_e32 v191, v193
	v_lshl_add_u64 v[202:203], v[82:83], 0, v[204:205]
	global_store_dwordx4 v[202:203], v[186:189], off sc1
	global_store_dwordx4 v[202:203], v[190:193], off offset:64 sc1
	v_lshl_add_u64 v[50:51], s[90:91], 0, v[102:103]
	s_and_saveexec_b64 s[38:39], s[8:9]
	s_cbranch_execz .LBB0_328
	s_lshl_b32 s16, s46, 2
	s_waitcnt lgkmcnt(0)
	v_add_f32_e32 v54, v52, v53
	v_lshl_add_u64 v[52:53], v[50:51], 0, s[16:17]
	v_lshl_add_u64 v[52:53], v[52:53], 0, v[148:149]
	global_store_dword v[52:53], v54, off sc1
.LBB0_328:
	s_or_b64 exec, exec, s[38:39]
	s_waitcnt vmcnt(17)
	v_pk_add_f32 v[46:47], v[46:47], v[142:143]
	v_pk_add_f32 v[48:49], v[48:49], v[144:145]
	s_waitcnt lgkmcnt(0)
	v_pk_mul_f32 v[52:53], v[46:47], v[46:47]
	v_cvt_pk_bf16_f32 v194, v46, v47
	v_cvt_pk_bf16_f32 v195, v48, v49
	s_waitcnt vmcnt(16)
	v_pk_add_f32 v[42:43], v[42:43], v[138:139]
	v_pk_add_f32 v[44:45], v[44:45], v[140:141]
	v_pk_mul_f32 v[46:47], v[42:43], v[42:43]
	v_pk_mul_f32 v[54:55], v[48:49], v[48:49]
	v_pk_mul_f32 v[48:49], v[44:45], v[44:45]
	v_cvt_pk_bf16_f32 v196, v42, v43
	v_add_f32_e32 v43, v46, v47
	v_add_f32_e32 v46, v52, v53
	s_waitcnt vmcnt(15)
	v_pk_add_f32 v[38:39], v[38:39], v[134:135]
	v_add_f32_e32 v43, v43, v48
	v_add_f32_e32 v46, v46, v54
	v_pk_add_f32 v[40:41], v[40:41], v[136:137]
	v_pk_mul_f32 v[56:57], v[38:39], v[38:39]
	s_waitcnt vmcnt(14)
	v_pk_add_f32 v[60:61], v[34:35], v[130:131]
	v_add_f32_e32 v43, v43, v49
	v_add_f32_e32 v46, v46, v55
	v_pk_mul_f32 v[58:59], v[40:41], v[40:41]
	v_pk_add_f32 v[36:37], v[36:37], v[132:133]
	v_pk_mul_f32 v[34:35], v[60:61], v[60:61]
	v_add_f32_e32 v43, v46, v43
	v_add_f32_e32 v46, v56, v57
	v_pk_mul_f32 v[62:63], v[36:37], v[36:37]
	v_add_f32_e32 v46, v46, v58
	v_add_f32_e32 v34, v34, v35
	v_add_f32_e32 v46, v46, v59
	v_add_f32_e32 v34, v34, v62
	v_add_f32_e32 v43, v43, v46
	v_add_f32_e32 v34, v34, v63
	v_add_f32_e32 v34, v43, v34
	ds_bpermute_b32 v35, v167, v34
	v_cvt_pk_bf16_f32 v197, v44, v45
	v_cvt_pk_bf16_f32 v198, v38, v39
	v_cvt_pk_bf16_f32 v199, v40, v41
	s_waitcnt lgkmcnt(0)
	v_add_f32_e32 v34, v34, v35
	ds_bpermute_b32 v35, v166, v34
	v_cvt_pk_bf16_f32 v200, v60, v61
	v_cvt_pk_bf16_f32 v201, v36, v37
	s_nop 1
	v_permlane16_swap_b32_e32 v194, v196
	v_permlane16_swap_b32_e32 v195, v197
	v_permlane16_swap_b32_e32 v198, v200
	v_permlane16_swap_b32_e32 v199, v201
	v_lshl_add_u64 v[202:203], v[82:83], 0, v[204:205]
	global_store_dwordx4 v[202:203], v[194:197], off offset:256 sc1
	global_store_dwordx4 v[202:203], v[198:201], off offset:320 sc1
	s_and_saveexec_b64 s[38:39], s[8:9]
	s_cbranch_execz .LBB0_330
	s_lshl_b32 s16, s46, 2
	s_waitcnt lgkmcnt(0)
	v_add_f32_e32 v36, v34, v35
	v_lshl_add_u64 v[34:35], v[50:51], 0, s[16:17]
	v_lshl_add_u64 v[34:35], v[34:35], 0, v[148:149]
	global_store_dword v[34:35], v36, off offset:8 sc1
.LBB0_330:
	s_or_b64 exec, exec, s[38:39]
	v_add_u32_e32 v50, 0x90, v152
	v_ashrrev_i32_e32 v51, 31, v50
	v_readlane_b32 s60, v249, 38
	s_waitcnt lgkmcnt(0)
	v_readlane_b32 s61, v249, 39
	v_lshlrev_b64 v[68:69], 11, v[50:51]
	v_lshlrev_b64 v[70:71], 6, v[50:51]
	v_lshl_add_u64 v[50:51], s[12:13], 0, v[68:69]
	v_lshl_add_u64 v[50:51], v[150:151], 1, v[50:51]
	v_readlane_b32 s62, v249, 40
	v_readlane_b32 s63, v249, 41
	v_readlane_b32 s64, v249, 42
	v_readlane_b32 s65, v249, 43
	v_readlane_b32 s66, v249, 44
	v_readlane_b32 s67, v249, 45
	v_readlane_b32 s68, v249, 46
	v_readlane_b32 s69, v249, 47
	v_readlane_b32 s70, v249, 48
	v_readlane_b32 s71, v249, 49
	v_readlane_b32 s72, v249, 50
	v_readlane_b32 s73, v249, 51
	v_readlane_b32 s74, v249, 52
	v_readlane_b32 s75, v249, 53
	s_waitcnt vmcnt(11)
	v_pk_add_f32 v[22:23], v[22:23], v[206:207]
	v_pk_add_f32 v[24:25], v[24:25], v[208:209]
	s_waitcnt vmcnt(10)
	v_pk_add_f32 v[26:27], v[26:27], v[210:211]
	v_pk_add_f32 v[28:29], v[28:29], v[212:213]
	s_waitcnt vmcnt(9)
	v_pk_add_f32 v[30:31], v[30:31], v[214:215]
	s_waitcnt vmcnt(8)
	v_pk_add_f32 v[206:207], v[20:21], v[220:221]
	v_pk_mul_f32 v[20:21], v[22:23], v[22:23]
	v_pk_mul_f32 v[208:209], v[24:25], v[24:25]
	v_cvt_pk_bf16_f32 v186, v22, v23
	v_cvt_pk_bf16_f32 v187, v24, v25
	v_pk_mul_f32 v[24:25], v[26:27], v[26:27]
	v_pk_add_f32 v[32:33], v[32:33], v[216:217]
	v_pk_add_f32 v[18:19], v[18:19], v[218:219]
	v_pk_mul_f32 v[210:211], v[28:29], v[28:29]
	v_cvt_pk_bf16_f32 v188, v26, v27
	v_cvt_pk_bf16_f32 v189, v28, v29
	v_pk_mul_f32 v[28:29], v[30:31], v[30:31]
	v_add_f32_e32 v24, v24, v25
	v_add_f32_e32 v20, v20, v21
	v_pk_mul_f32 v[212:213], v[32:33], v[32:33]
	v_pk_mul_f32 v[214:215], v[18:19], v[18:19]
	v_add_f32_e32 v21, v28, v29
	v_add_f32_e32 v24, v24, v210
	v_add_f32_e32 v20, v20, v208
	v_pk_mul_f32 v[216:217], v[206:207], v[206:207]
	v_add_f32_e32 v25, v214, v215
	v_add_f32_e32 v21, v21, v212
	v_add_f32_e32 v24, v24, v211
	v_add_f32_e32 v20, v20, v209
	v_add_f32_e32 v25, v25, v216
	v_add_f32_e32 v21, v21, v213
	v_add_f32_e32 v20, v20, v24
	v_add_f32_e32 v20, v20, v21
	v_add_f32_e32 v21, v25, v217
	v_add_f32_e32 v20, v20, v21
	ds_bpermute_b32 v21, v167, v20
	v_cvt_pk_bf16_f32 v192, v18, v19
	v_cvt_pk_bf16_f32 v193, v206, v207
	v_cvt_pk_bf16_f32 v190, v30, v31
	v_cvt_pk_bf16_f32 v191, v32, v33
	s_waitcnt lgkmcnt(0)
	v_add_f32_e32 v20, v20, v21
	ds_bpermute_b32 v21, v166, v20
	s_nop 1
	v_permlane16_swap_b32_e32 v186, v188
	v_permlane16_swap_b32_e32 v187, v189
	v_permlane16_swap_b32_e32 v190, v192
	v_permlane16_swap_b32_e32 v191, v193
	v_lshl_add_u64 v[202:203], v[50:51], 0, v[204:205]
	global_store_dwordx4 v[202:203], v[186:189], off sc1
	global_store_dwordx4 v[202:203], v[190:193], off offset:64 sc1
	v_lshl_add_u64 v[18:19], s[90:91], 0, v[70:71]
	s_and_saveexec_b64 s[38:39], s[8:9]
	s_cbranch_execz .LBB0_332
	s_lshl_b32 s16, s46, 2
	s_waitcnt lgkmcnt(0)
	v_add_f32_e32 v22, v20, v21
	v_lshl_add_u64 v[20:21], v[18:19], 0, s[16:17]
	v_lshl_add_u64 v[20:21], v[20:21], 0, v[148:149]
	global_store_dword v[20:21], v22, off sc1
.LBB0_332:
	s_or_b64 exec, exec, s[38:39]
	s_waitcnt vmcnt(9)
	v_pk_add_f32 v[14:15], v[14:15], v[222:223]
	v_pk_add_f32 v[16:17], v[16:17], v[224:225]
	s_waitcnt lgkmcnt(0)
	v_pk_mul_f32 v[20:21], v[14:15], v[14:15]
	v_cvt_pk_bf16_f32 v194, v14, v15
	v_cvt_pk_bf16_f32 v195, v16, v17
	s_waitcnt vmcnt(8)
	v_pk_add_f32 v[10:11], v[10:11], v[226:227]
	v_pk_add_f32 v[12:13], v[12:13], v[228:229]
	v_pk_mul_f32 v[14:15], v[10:11], v[10:11]
	v_pk_mul_f32 v[22:23], v[16:17], v[16:17]
	v_pk_mul_f32 v[16:17], v[12:13], v[12:13]
	v_cvt_pk_bf16_f32 v196, v10, v11
	v_add_f32_e32 v11, v14, v15
	v_add_f32_e32 v14, v20, v21
	s_waitcnt vmcnt(7)
	v_pk_add_f32 v[6:7], v[6:7], v[230:231]
	v_add_f32_e32 v11, v11, v16
	v_add_f32_e32 v14, v14, v22
	v_pk_add_f32 v[8:9], v[8:9], v[232:233]
	v_pk_mul_f32 v[24:25], v[6:7], v[6:7]
	s_waitcnt vmcnt(6)
	v_pk_add_f32 v[28:29], v[2:3], v[234:235]
	v_add_f32_e32 v11, v11, v17
	v_add_f32_e32 v14, v14, v23
	v_pk_mul_f32 v[26:27], v[8:9], v[8:9]
	v_pk_add_f32 v[4:5], v[4:5], v[236:237]
	v_pk_mul_f32 v[2:3], v[28:29], v[28:29]
	v_add_f32_e32 v11, v14, v11
	v_add_f32_e32 v14, v24, v25
	v_pk_mul_f32 v[30:31], v[4:5], v[4:5]
	v_add_f32_e32 v14, v14, v26
	v_add_f32_e32 v2, v2, v3
	v_add_f32_e32 v14, v14, v27
	v_add_f32_e32 v2, v2, v30
	v_add_f32_e32 v11, v11, v14
	v_add_f32_e32 v2, v2, v31
	v_add_f32_e32 v2, v11, v2
	ds_bpermute_b32 v3, v167, v2
	v_cvt_pk_bf16_f32 v197, v12, v13
	v_cvt_pk_bf16_f32 v198, v6, v7
	v_cvt_pk_bf16_f32 v199, v8, v9
	s_waitcnt lgkmcnt(0)
	v_add_f32_e32 v2, v2, v3
	ds_bpermute_b32 v3, v166, v2
	v_cvt_pk_bf16_f32 v200, v28, v29
	v_cvt_pk_bf16_f32 v201, v4, v5
	s_nop 1
	v_permlane16_swap_b32_e32 v194, v196
	v_permlane16_swap_b32_e32 v195, v197
	v_permlane16_swap_b32_e32 v198, v200
	v_permlane16_swap_b32_e32 v199, v201
	v_lshl_add_u64 v[202:203], v[50:51], 0, v[204:205]
	global_store_dwordx4 v[202:203], v[194:197], off offset:256 sc1
	global_store_dwordx4 v[202:203], v[198:201], off offset:320 sc1
	s_and_saveexec_b64 s[38:39], s[8:9]
	s_cbranch_execz .LBB0_334
	s_lshl_b32 s16, s46, 2
	s_waitcnt lgkmcnt(0)
	v_add_f32_e32 v4, v2, v3
	v_lshl_add_u64 v[2:3], v[18:19], 0, s[16:17]
	v_lshl_add_u64 v[2:3], v[2:3], 0, v[148:149]
	global_store_dword v[2:3], v4, off offset:8 sc1
